# GRES epilogue stores (now full 128B lines) marked nt
# baseline (speedup 1.0000x reference)
;     __device__ __forceinline__ void operator()(const f32x4 (&acc)[2][2][4][2], const pg8::Unit& u, int wr, int wc, int fr, int fq) const {
;         const int R0 = row_off + u.pm * 256;
;         const float* inp; float* outp; int bidx;
;         if (R0 < ML) { bidx = R0 >> 12; inp = in_lat + (size_t)R0 * DM; outp = out_lat + (size_t)R0 * DM; }
;         else { bidx = 8; inp = in_ctx + (size_t)(R0 - ML) * DM; outp = out_ctx + (size_t)(R0 - ML) * DM; }
;         const int col0 = u.pn * 256 + wc * 32 + 4 * fq;
;         const float* gp = gate + (size_t)bidx * 6144 + col0;
;         f32x4 gv[2][2];
; #pragma unroll
;         for (int bj = 0; bj < 2; ++bj)
; #pragma unroll
;             for (int n = 0; n < 2; ++n) gv[bj][n] = *(const f32x4*)(gp + bj * 128 + n * 16);
; #pragma unroll
;         for (int ai = 0; ai < 2; ++ai)
; #pragma unroll
;             for (int m = 0; m < 4; ++m) { const size_t ro = (size_t)(wr * 64 + fr + ai * 128 + m * 16) * DM + col0;
; #pragma unroll
;                 for (int bj = 0; bj < 2; ++bj)
; #pragma unroll
;                     for (int n = 0; n < 2; ++n) { const size_t o = ro + bj * 128 + n * 16; *(f32x4*)(outp + o) = *(const f32x4*)(inp + o) + gv[bj][n] * acc[ai][bj][m][n]; } }
.LBB0_256:
	v_lshl_or_b32 v168, s70, 8, v171
	s_lshl_b64 s[22:23], s[24:25], 2
	v_ashrrev_i32_e32 v169, 31, v168
	s_add_u32 s22, s46, s22
	s_addc_u32 s23, s47, s23
	v_lshl_add_u64 v[130:131], v[168:169], 2, s[22:23]
	global_load_dwordx4 v[142:145], v[130:131], off
	global_load_dwordx4 v[138:141], v[130:131], off offset:64
	global_load_dwordx4 v[134:137], v[130:131], off offset:512
	s_nop 0
	global_load_dwordx4 v[130:133], v[130:131], off offset:576
	s_mov_b32 s70, s67
	s_mov_b32 s69, s68
	v_and_b32_e32 v173, 8, v220
	v_mul_i32_i24_e32 v173, 0xfffff008, v173
	v_cmp_eq_u32_e64 s[22:23], 0, v173
	v_add_lshl_u32 v176, v148, v168, 2
	v_add_lshl_u32 v177, v150, v168, 2
	v_add_lshl_u32 v178, v152, v168, 2
	v_add_lshl_u32 v179, v154, v168, 2
	v_add_lshl_u32 v180, v156, v168, 2
	v_add_lshl_u32 v181, v158, v168, 2
	v_add_lshl_u32 v182, v160, v168, 2
	v_add_lshl_u32 v183, v162, v168, 2
	v_add_u32_e32 v176, v176, v173
	v_add_u32_e32 v177, v177, v173
	v_add_u32_e32 v178, v178, v173
	v_add_u32_e32 v179, v179, v173
	v_add_u32_e32 v180, v180, v173
	v_add_u32_e32 v181, v181, v173
	v_add_u32_e32 v182, v182, v173
	v_add_u32_e32 v183, v183, v173
	v_add_u32_e32 v184, 0x8000, v176
	v_add_u32_e32 v185, 0x8000, v177
	v_add_u32_e32 v186, 0x8000, v178
	v_add_u32_e32 v187, 0x8000, v179
	v_add_u32_e32 v188, 0x8000, v180
	v_add_u32_e32 v189, 0x8000, v181
	v_add_u32_e32 v190, 0x8000, v182
	v_add_u32_e32 v191, 0x8000, v183
	global_load_dwordx4 v[192:195], v176, s[20:21]
	global_load_dwordx4 v[196:199], v184, s[20:21]
	global_load_dwordx4 v[200:203], v176, s[20:21] offset:512
	global_load_dwordx4 v[204:207], v184, s[20:21] offset:512
	global_load_dwordx4 v[208:211], v177, s[20:21]
	global_load_dwordx4 v[212:215], v185, s[20:21]
	global_load_dwordx4 v[216:219], v177, s[20:21] offset:512
	global_load_dwordx4 v[234:237], v185, s[20:21] offset:512
	global_load_dwordx4 v[238:241], v178, s[20:21]
	v_mov_b32_dpp v224, v126 row_ror:8 row_mask:0xf bank_mask:0x3
	v_mov_b32_dpp v225, v127 row_ror:8 row_mask:0xf bank_mask:0x3
	v_mov_b32_dpp v228, v128 row_ror:8 row_mask:0xf bank_mask:0x3
	v_mov_b32_dpp v229, v129 row_ror:8 row_mask:0xf bank_mask:0x3
	v_mov_b32_dpp v126, v122 row_ror:8 row_mask:0xf bank_mask:0xc
	v_mov_b32_dpp v127, v123 row_ror:8 row_mask:0xf bank_mask:0xc
	v_mov_b32_dpp v128, v124 row_ror:8 row_mask:0xf bank_mask:0xc
	v_mov_b32_dpp v129, v125 row_ror:8 row_mask:0xf bank_mask:0xc
	v_mov_b32_dpp v122, v224 quad_perm:[0,1,2,3] row_mask:0xf bank_mask:0x3
	v_mov_b32_dpp v123, v225 quad_perm:[0,1,2,3] row_mask:0xf bank_mask:0x3
	v_mov_b32_dpp v124, v228 quad_perm:[0,1,2,3] row_mask:0xf bank_mask:0x3
	v_mov_b32_dpp v125, v229 quad_perm:[0,1,2,3] row_mask:0xf bank_mask:0x3
	v_mov_b32_dpp v224, v118 row_ror:8 row_mask:0xf bank_mask:0x3
	v_mov_b32_dpp v225, v119 row_ror:8 row_mask:0xf bank_mask:0x3
	v_mov_b32_dpp v228, v120 row_ror:8 row_mask:0xf bank_mask:0x3
	v_mov_b32_dpp v229, v121 row_ror:8 row_mask:0xf bank_mask:0x3
	v_mov_b32_dpp v118, v106 row_ror:8 row_mask:0xf bank_mask:0xc
	v_mov_b32_dpp v119, v107 row_ror:8 row_mask:0xf bank_mask:0xc
	v_mov_b32_dpp v120, v108 row_ror:8 row_mask:0xf bank_mask:0xc
	v_mov_b32_dpp v121, v109 row_ror:8 row_mask:0xf bank_mask:0xc
	v_mov_b32_dpp v106, v224 quad_perm:[0,1,2,3] row_mask:0xf bank_mask:0x3
	v_mov_b32_dpp v107, v225 quad_perm:[0,1,2,3] row_mask:0xf bank_mask:0x3
	v_mov_b32_dpp v108, v228 quad_perm:[0,1,2,3] row_mask:0xf bank_mask:0x3
	v_mov_b32_dpp v109, v229 quad_perm:[0,1,2,3] row_mask:0xf bank_mask:0x3
	v_mov_b32_dpp v224, v114 row_ror:8 row_mask:0xf bank_mask:0x3
	v_mov_b32_dpp v225, v115 row_ror:8 row_mask:0xf bank_mask:0x3
	v_mov_b32_dpp v228, v116 row_ror:8 row_mask:0xf bank_mask:0x3
	v_mov_b32_dpp v229, v117 row_ror:8 row_mask:0xf bank_mask:0x3
	v_mov_b32_dpp v114, v110 row_ror:8 row_mask:0xf bank_mask:0xc
	v_mov_b32_dpp v115, v111 row_ror:8 row_mask:0xf bank_mask:0xc
	v_mov_b32_dpp v116, v112 row_ror:8 row_mask:0xf bank_mask:0xc
	v_mov_b32_dpp v117, v113 row_ror:8 row_mask:0xf bank_mask:0xc
	v_mov_b32_dpp v110, v224 quad_perm:[0,1,2,3] row_mask:0xf bank_mask:0x3
	v_mov_b32_dpp v111, v225 quad_perm:[0,1,2,3] row_mask:0xf bank_mask:0x3
	v_mov_b32_dpp v112, v228 quad_perm:[0,1,2,3] row_mask:0xf bank_mask:0x3
	v_mov_b32_dpp v113, v229 quad_perm:[0,1,2,3] row_mask:0xf bank_mask:0x3
	v_mov_b32_dpp v224, v102 row_ror:8 row_mask:0xf bank_mask:0x3
	v_mov_b32_dpp v225, v103 row_ror:8 row_mask:0xf bank_mask:0x3
	v_mov_b32_dpp v228, v104 row_ror:8 row_mask:0xf bank_mask:0x3
	v_mov_b32_dpp v229, v105 row_ror:8 row_mask:0xf bank_mask:0x3
	v_mov_b32_dpp v102, v90 row_ror:8 row_mask:0xf bank_mask:0xc
	v_mov_b32_dpp v103, v91 row_ror:8 row_mask:0xf bank_mask:0xc
	v_mov_b32_dpp v104, v92 row_ror:8 row_mask:0xf bank_mask:0xc
	v_mov_b32_dpp v105, v93 row_ror:8 row_mask:0xf bank_mask:0xc
	v_mov_b32_dpp v90, v224 quad_perm:[0,1,2,3] row_mask:0xf bank_mask:0x3
	v_mov_b32_dpp v91, v225 quad_perm:[0,1,2,3] row_mask:0xf bank_mask:0x3
	v_mov_b32_dpp v92, v228 quad_perm:[0,1,2,3] row_mask:0xf bank_mask:0x3
	v_mov_b32_dpp v93, v229 quad_perm:[0,1,2,3] row_mask:0xf bank_mask:0x3
	v_mov_b32_dpp v224, v98 row_ror:8 row_mask:0xf bank_mask:0x3
	v_mov_b32_dpp v225, v99 row_ror:8 row_mask:0xf bank_mask:0x3
	v_mov_b32_dpp v228, v100 row_ror:8 row_mask:0xf bank_mask:0x3
	v_mov_b32_dpp v229, v101 row_ror:8 row_mask:0xf bank_mask:0x3
	v_mov_b32_dpp v98, v94 row_ror:8 row_mask:0xf bank_mask:0xc
	v_mov_b32_dpp v99, v95 row_ror:8 row_mask:0xf bank_mask:0xc
	v_mov_b32_dpp v100, v96 row_ror:8 row_mask:0xf bank_mask:0xc
	v_mov_b32_dpp v101, v97 row_ror:8 row_mask:0xf bank_mask:0xc
	v_mov_b32_dpp v94, v224 quad_perm:[0,1,2,3] row_mask:0xf bank_mask:0x3
;     __device__ __forceinline__ void operator()(const f32x4 (&acc)[2][2][4][2], const pg8::Unit& u, int wr, int wc, int fr, int fq) const {
;     ...
;         for (int ai = 0; ai < 2; ++ai)
; #pragma unroll
;             for (int m = 0; m < 4; ++m) { const size_t ro = (size_t)(wr * 64 + fr + ai * 128 + m * 16) * DM + col0;
; #pragma unroll
;                 for (int bj = 0; bj < 2; ++bj)
; #pragma unroll
;                     for (int n = 0; n < 2; ++n) { const size_t o = ro + bj * 128 + n * 16; *(f32x4*)(outp + o) = *(const f32x4*)(inp + o) + gv[bj][n] * acc[ai][bj][m][n]; } }
	v_mov_b32_dpp v95, v225 quad_perm:[0,1,2,3] row_mask:0xf bank_mask:0x3
	v_mov_b32_dpp v96, v228 quad_perm:[0,1,2,3] row_mask:0xf bank_mask:0x3
	v_mov_b32_dpp v97, v229 quad_perm:[0,1,2,3] row_mask:0xf bank_mask:0x3
	v_mov_b32_dpp v224, v86 row_ror:8 row_mask:0xf bank_mask:0x3
	v_mov_b32_dpp v225, v87 row_ror:8 row_mask:0xf bank_mask:0x3
	v_mov_b32_dpp v228, v88 row_ror:8 row_mask:0xf bank_mask:0x3
	v_mov_b32_dpp v229, v89 row_ror:8 row_mask:0xf bank_mask:0x3
	v_mov_b32_dpp v86, v74 row_ror:8 row_mask:0xf bank_mask:0xc
	v_mov_b32_dpp v87, v75 row_ror:8 row_mask:0xf bank_mask:0xc
	v_mov_b32_dpp v88, v76 row_ror:8 row_mask:0xf bank_mask:0xc
	v_mov_b32_dpp v89, v77 row_ror:8 row_mask:0xf bank_mask:0xc
	v_mov_b32_dpp v74, v224 quad_perm:[0,1,2,3] row_mask:0xf bank_mask:0x3
	v_mov_b32_dpp v75, v225 quad_perm:[0,1,2,3] row_mask:0xf bank_mask:0x3
	v_mov_b32_dpp v76, v228 quad_perm:[0,1,2,3] row_mask:0xf bank_mask:0x3
	v_mov_b32_dpp v77, v229 quad_perm:[0,1,2,3] row_mask:0xf bank_mask:0x3
	v_mov_b32_dpp v224, v82 row_ror:8 row_mask:0xf bank_mask:0x3
	v_mov_b32_dpp v225, v83 row_ror:8 row_mask:0xf bank_mask:0x3
	v_mov_b32_dpp v228, v84 row_ror:8 row_mask:0xf bank_mask:0x3
	v_mov_b32_dpp v229, v85 row_ror:8 row_mask:0xf bank_mask:0x3
	v_mov_b32_dpp v82, v78 row_ror:8 row_mask:0xf bank_mask:0xc
	v_mov_b32_dpp v83, v79 row_ror:8 row_mask:0xf bank_mask:0xc
	v_mov_b32_dpp v84, v80 row_ror:8 row_mask:0xf bank_mask:0xc
	v_mov_b32_dpp v85, v81 row_ror:8 row_mask:0xf bank_mask:0xc
	v_mov_b32_dpp v78, v224 quad_perm:[0,1,2,3] row_mask:0xf bank_mask:0x3
	v_mov_b32_dpp v79, v225 quad_perm:[0,1,2,3] row_mask:0xf bank_mask:0x3
	v_mov_b32_dpp v80, v228 quad_perm:[0,1,2,3] row_mask:0xf bank_mask:0x3
	v_mov_b32_dpp v81, v229 quad_perm:[0,1,2,3] row_mask:0xf bank_mask:0x3
	v_mov_b32_dpp v224, v70 row_ror:8 row_mask:0xf bank_mask:0x3
	v_mov_b32_dpp v225, v71 row_ror:8 row_mask:0xf bank_mask:0x3
	v_mov_b32_dpp v228, v72 row_ror:8 row_mask:0xf bank_mask:0x3
	v_mov_b32_dpp v229, v73 row_ror:8 row_mask:0xf bank_mask:0x3
	v_mov_b32_dpp v70, v66 row_ror:8 row_mask:0xf bank_mask:0xc
	v_mov_b32_dpp v71, v67 row_ror:8 row_mask:0xf bank_mask:0xc
	v_mov_b32_dpp v72, v68 row_ror:8 row_mask:0xf bank_mask:0xc
	v_mov_b32_dpp v73, v69 row_ror:8 row_mask:0xf bank_mask:0xc
	v_mov_b32_dpp v66, v224 quad_perm:[0,1,2,3] row_mask:0xf bank_mask:0x3
	v_mov_b32_dpp v67, v225 quad_perm:[0,1,2,3] row_mask:0xf bank_mask:0x3
	v_mov_b32_dpp v68, v228 quad_perm:[0,1,2,3] row_mask:0xf bank_mask:0x3
	v_mov_b32_dpp v69, v229 quad_perm:[0,1,2,3] row_mask:0xf bank_mask:0x3
	v_mov_b32_dpp v224, v62 row_ror:8 row_mask:0xf bank_mask:0x3
	v_mov_b32_dpp v225, v63 row_ror:8 row_mask:0xf bank_mask:0x3
	v_mov_b32_dpp v228, v64 row_ror:8 row_mask:0xf bank_mask:0x3
	v_mov_b32_dpp v229, v65 row_ror:8 row_mask:0xf bank_mask:0x3
	v_mov_b32_dpp v62, v58 row_ror:8 row_mask:0xf bank_mask:0xc
	v_mov_b32_dpp v63, v59 row_ror:8 row_mask:0xf bank_mask:0xc
	v_mov_b32_dpp v64, v60 row_ror:8 row_mask:0xf bank_mask:0xc
	v_mov_b32_dpp v65, v61 row_ror:8 row_mask:0xf bank_mask:0xc
	v_mov_b32_dpp v58, v224 quad_perm:[0,1,2,3] row_mask:0xf bank_mask:0x3
	v_mov_b32_dpp v59, v225 quad_perm:[0,1,2,3] row_mask:0xf bank_mask:0x3
	v_mov_b32_dpp v60, v228 quad_perm:[0,1,2,3] row_mask:0xf bank_mask:0x3
	v_mov_b32_dpp v61, v229 quad_perm:[0,1,2,3] row_mask:0xf bank_mask:0x3
	v_mov_b32_dpp v224, v54 row_ror:8 row_mask:0xf bank_mask:0x3
	v_mov_b32_dpp v225, v55 row_ror:8 row_mask:0xf bank_mask:0x3
	v_mov_b32_dpp v228, v56 row_ror:8 row_mask:0xf bank_mask:0x3
	v_mov_b32_dpp v229, v57 row_ror:8 row_mask:0xf bank_mask:0x3
	v_mov_b32_dpp v54, v40 row_ror:8 row_mask:0xf bank_mask:0xc
	v_mov_b32_dpp v55, v41 row_ror:8 row_mask:0xf bank_mask:0xc
	v_mov_b32_dpp v56, v42 row_ror:8 row_mask:0xf bank_mask:0xc
	v_mov_b32_dpp v57, v43 row_ror:8 row_mask:0xf bank_mask:0xc
	v_mov_b32_dpp v40, v224 quad_perm:[0,1,2,3] row_mask:0xf bank_mask:0x3
	v_mov_b32_dpp v41, v225 quad_perm:[0,1,2,3] row_mask:0xf bank_mask:0x3
	v_mov_b32_dpp v42, v228 quad_perm:[0,1,2,3] row_mask:0xf bank_mask:0x3
	v_mov_b32_dpp v43, v229 quad_perm:[0,1,2,3] row_mask:0xf bank_mask:0x3
	v_mov_b32_dpp v224, v50 row_ror:8 row_mask:0xf bank_mask:0x3
	v_mov_b32_dpp v225, v51 row_ror:8 row_mask:0xf bank_mask:0x3
	v_mov_b32_dpp v228, v52 row_ror:8 row_mask:0xf bank_mask:0x3
	v_mov_b32_dpp v229, v53 row_ror:8 row_mask:0xf bank_mask:0x3
	v_mov_b32_dpp v50, v44 row_ror:8 row_mask:0xf bank_mask:0xc
	v_mov_b32_dpp v51, v45 row_ror:8 row_mask:0xf bank_mask:0xc
	v_mov_b32_dpp v52, v46 row_ror:8 row_mask:0xf bank_mask:0xc
	v_mov_b32_dpp v53, v47 row_ror:8 row_mask:0xf bank_mask:0xc
	v_mov_b32_dpp v44, v224 quad_perm:[0,1,2,3] row_mask:0xf bank_mask:0x3
	v_mov_b32_dpp v45, v225 quad_perm:[0,1,2,3] row_mask:0xf bank_mask:0x3
	v_mov_b32_dpp v46, v228 quad_perm:[0,1,2,3] row_mask:0xf bank_mask:0x3
	v_mov_b32_dpp v47, v229 quad_perm:[0,1,2,3] row_mask:0xf bank_mask:0x3
	v_mov_b32_dpp v224, v36 row_ror:8 row_mask:0xf bank_mask:0x3
	v_mov_b32_dpp v225, v37 row_ror:8 row_mask:0xf bank_mask:0x3
	v_mov_b32_dpp v228, v38 row_ror:8 row_mask:0xf bank_mask:0x3
	v_mov_b32_dpp v229, v39 row_ror:8 row_mask:0xf bank_mask:0x3
	v_mov_b32_dpp v36, v24 row_ror:8 row_mask:0xf bank_mask:0xc
	v_mov_b32_dpp v37, v25 row_ror:8 row_mask:0xf bank_mask:0xc
	v_mov_b32_dpp v38, v26 row_ror:8 row_mask:0xf bank_mask:0xc
	v_mov_b32_dpp v39, v27 row_ror:8 row_mask:0xf bank_mask:0xc
	v_mov_b32_dpp v24, v224 quad_perm:[0,1,2,3] row_mask:0xf bank_mask:0x3
	v_mov_b32_dpp v25, v225 quad_perm:[0,1,2,3] row_mask:0xf bank_mask:0x3
	v_mov_b32_dpp v26, v228 quad_perm:[0,1,2,3] row_mask:0xf bank_mask:0x3
;     __device__ __forceinline__ void operator()(const f32x4 (&acc)[2][2][4][2], const pg8::Unit& u, int wr, int wc, int fr, int fq) const {
;     ...
;         for (int ai = 0; ai < 2; ++ai)
; #pragma unroll
;             for (int m = 0; m < 4; ++m) { const size_t ro = (size_t)(wr * 64 + fr + ai * 128 + m * 16) * DM + col0;
; #pragma unroll
;                 for (int bj = 0; bj < 2; ++bj)
; #pragma unroll
;                     for (int n = 0; n < 2; ++n) { const size_t o = ro + bj * 128 + n * 16; *(f32x4*)(outp + o) = *(const f32x4*)(inp + o) + gv[bj][n] * acc[ai][bj][m][n]; } }
	v_mov_b32_dpp v27, v229 quad_perm:[0,1,2,3] row_mask:0xf bank_mask:0x3
	v_mov_b32_dpp v224, v32 row_ror:8 row_mask:0xf bank_mask:0x3
	v_mov_b32_dpp v225, v33 row_ror:8 row_mask:0xf bank_mask:0x3
	v_mov_b32_dpp v228, v34 row_ror:8 row_mask:0xf bank_mask:0x3
	v_mov_b32_dpp v229, v35 row_ror:8 row_mask:0xf bank_mask:0x3
	v_mov_b32_dpp v32, v28 row_ror:8 row_mask:0xf bank_mask:0xc
	v_mov_b32_dpp v33, v29 row_ror:8 row_mask:0xf bank_mask:0xc
	v_mov_b32_dpp v34, v30 row_ror:8 row_mask:0xf bank_mask:0xc
	v_mov_b32_dpp v35, v31 row_ror:8 row_mask:0xf bank_mask:0xc
	v_mov_b32_dpp v28, v224 quad_perm:[0,1,2,3] row_mask:0xf bank_mask:0x3
	v_mov_b32_dpp v29, v225 quad_perm:[0,1,2,3] row_mask:0xf bank_mask:0x3
	v_mov_b32_dpp v30, v228 quad_perm:[0,1,2,3] row_mask:0xf bank_mask:0x3
	v_mov_b32_dpp v31, v229 quad_perm:[0,1,2,3] row_mask:0xf bank_mask:0x3
	v_mov_b32_dpp v224, v20 row_ror:8 row_mask:0xf bank_mask:0x3
	v_mov_b32_dpp v225, v21 row_ror:8 row_mask:0xf bank_mask:0x3
	v_mov_b32_dpp v228, v22 row_ror:8 row_mask:0xf bank_mask:0x3
	v_mov_b32_dpp v229, v23 row_ror:8 row_mask:0xf bank_mask:0x3
	v_mov_b32_dpp v20, v8 row_ror:8 row_mask:0xf bank_mask:0xc
	v_mov_b32_dpp v21, v9 row_ror:8 row_mask:0xf bank_mask:0xc
	v_mov_b32_dpp v22, v10 row_ror:8 row_mask:0xf bank_mask:0xc
	v_mov_b32_dpp v23, v11 row_ror:8 row_mask:0xf bank_mask:0xc
	v_mov_b32_dpp v8, v224 quad_perm:[0,1,2,3] row_mask:0xf bank_mask:0x3
	v_mov_b32_dpp v9, v225 quad_perm:[0,1,2,3] row_mask:0xf bank_mask:0x3
	v_mov_b32_dpp v10, v228 quad_perm:[0,1,2,3] row_mask:0xf bank_mask:0x3
	v_mov_b32_dpp v11, v229 quad_perm:[0,1,2,3] row_mask:0xf bank_mask:0x3
	v_mov_b32_dpp v224, v16 row_ror:8 row_mask:0xf bank_mask:0x3
	v_mov_b32_dpp v225, v17 row_ror:8 row_mask:0xf bank_mask:0x3
	v_mov_b32_dpp v228, v18 row_ror:8 row_mask:0xf bank_mask:0x3
	v_mov_b32_dpp v229, v19 row_ror:8 row_mask:0xf bank_mask:0x3
	v_mov_b32_dpp v16, v12 row_ror:8 row_mask:0xf bank_mask:0xc
	v_mov_b32_dpp v17, v13 row_ror:8 row_mask:0xf bank_mask:0xc
	v_mov_b32_dpp v18, v14 row_ror:8 row_mask:0xf bank_mask:0xc
	v_mov_b32_dpp v19, v15 row_ror:8 row_mask:0xf bank_mask:0xc
	v_mov_b32_dpp v12, v224 quad_perm:[0,1,2,3] row_mask:0xf bank_mask:0x3
	v_mov_b32_dpp v13, v225 quad_perm:[0,1,2,3] row_mask:0xf bank_mask:0x3
	v_mov_b32_dpp v14, v228 quad_perm:[0,1,2,3] row_mask:0xf bank_mask:0x3
	v_mov_b32_dpp v15, v229 quad_perm:[0,1,2,3] row_mask:0xf bank_mask:0x3
	v_mov_b32_dpp v224, v4 row_ror:8 row_mask:0xf bank_mask:0x3
	v_mov_b32_dpp v225, v5 row_ror:8 row_mask:0xf bank_mask:0x3
	v_mov_b32_dpp v228, v6 row_ror:8 row_mask:0xf bank_mask:0x3
	v_mov_b32_dpp v229, v7 row_ror:8 row_mask:0xf bank_mask:0x3
	v_mov_b32_dpp v4, v0 row_ror:8 row_mask:0xf bank_mask:0xc
	v_mov_b32_dpp v5, v1 row_ror:8 row_mask:0xf bank_mask:0xc
	v_mov_b32_dpp v6, v2 row_ror:8 row_mask:0xf bank_mask:0xc
	v_mov_b32_dpp v7, v3 row_ror:8 row_mask:0xf bank_mask:0xc
	v_mov_b32_dpp v0, v224 quad_perm:[0,1,2,3] row_mask:0xf bank_mask:0x3
	v_mov_b32_dpp v1, v225 quad_perm:[0,1,2,3] row_mask:0xf bank_mask:0x3
	v_mov_b32_dpp v2, v228 quad_perm:[0,1,2,3] row_mask:0xf bank_mask:0x3
	v_mov_b32_dpp v3, v229 quad_perm:[0,1,2,3] row_mask:0xf bank_mask:0x3
	s_waitcnt vmcnt(9)
	v_cndmask_b32_e64 v142, v138, v142, s[22:23]
	v_cndmask_b32_e64 v143, v139, v143, s[22:23]
	v_cndmask_b32_e64 v144, v140, v144, s[22:23]
	v_cndmask_b32_e64 v145, v141, v145, s[22:23]
	v_cndmask_b32_e64 v134, v130, v134, s[22:23]
	v_cndmask_b32_e64 v135, v131, v135, s[22:23]
	v_cndmask_b32_e64 v136, v132, v136, s[22:23]
	v_cndmask_b32_e64 v137, v133, v137, s[22:23]
	s_waitcnt vmcnt(8)
	v_pk_fma_f32 v[128:129], v[128:129], v[144:145], v[194:195]
	v_pk_fma_f32 v[126:127], v[126:127], v[142:143], v[192:193]
	global_load_dwordx4 v[192:195], v186, s[20:21]
	global_store_dwordx4 v176, v[126:129], s[16:17] nt
	s_waitcnt vmcnt(9)
	v_pk_fma_f32 v[124:125], v[124:125], v[144:145], v[198:199]
	v_pk_fma_f32 v[122:123], v[122:123], v[142:143], v[196:197]
	global_load_dwordx4 v[196:199], v178, s[20:21] offset:512
	global_store_dwordx4 v184, v[122:125], s[16:17] nt
	s_waitcnt vmcnt(10)
	v_pk_fma_f32 v[120:121], v[120:121], v[136:137], v[202:203]
	v_pk_fma_f32 v[118:119], v[118:119], v[134:135], v[200:201]
	global_load_dwordx4 v[200:203], v186, s[20:21] offset:512
	global_store_dwordx4 v176, v[118:121], s[16:17] offset:512 nt
	s_waitcnt vmcnt(11)
	v_pk_fma_f32 v[108:109], v[108:109], v[136:137], v[206:207]
	v_pk_fma_f32 v[106:107], v[106:107], v[134:135], v[204:205]
	global_load_dwordx4 v[204:207], v179, s[20:21]
	global_store_dwordx4 v184, v[106:109], s[16:17] offset:512 nt
	s_waitcnt vmcnt(12)
	v_pk_fma_f32 v[116:117], v[116:117], v[144:145], v[210:211]
	v_pk_fma_f32 v[114:115], v[114:115], v[142:143], v[208:209]
	global_load_dwordx4 v[208:211], v187, s[20:21]
	global_store_dwordx4 v177, v[114:117], s[16:17] nt
	s_waitcnt vmcnt(13)
	v_pk_fma_f32 v[112:113], v[112:113], v[144:145], v[214:215]
	v_pk_fma_f32 v[110:111], v[110:111], v[142:143], v[212:213]
	global_load_dwordx4 v[212:215], v179, s[20:21] offset:512
	global_store_dwordx4 v185, v[110:113], s[16:17] nt
	s_waitcnt vmcnt(14)
	v_pk_fma_f32 v[104:105], v[104:105], v[136:137], v[218:219]
	v_pk_fma_f32 v[102:103], v[102:103], v[134:135], v[216:217]
	global_load_dwordx4 v[216:219], v187, s[20:21] offset:512
	global_store_dwordx4 v177, v[102:105], s[16:17] offset:512 nt
	s_waitcnt vmcnt(15)
	v_pk_fma_f32 v[92:93], v[92:93], v[136:137], v[236:237]
	v_pk_fma_f32 v[90:91], v[90:91], v[134:135], v[234:235]
	global_load_dwordx4 v[234:237], v180, s[20:21]
	global_store_dwordx4 v185, v[90:93], s[16:17] offset:512 nt
	s_waitcnt vmcnt(16)
;     __device__ __forceinline__ void operator()(const f32x4 (&acc)[2][2][4][2], const pg8::Unit& u, int wr, int wc, int fr, int fq) const {
;     ...
;         for (int ai = 0; ai < 2; ++ai)
; #pragma unroll
;             for (int m = 0; m < 4; ++m) { const size_t ro = (size_t)(wr * 64 + fr + ai * 128 + m * 16) * DM + col0;
; #pragma unroll
;                 for (int bj = 0; bj < 2; ++bj)
; #pragma unroll
;                     for (int n = 0; n < 2; ++n) { const size_t o = ro + bj * 128 + n * 16; *(f32x4*)(outp + o) = *(const f32x4*)(inp + o) + gv[bj][n] * acc[ai][bj][m][n]; } }
	v_pk_fma_f32 v[100:101], v[100:101], v[144:145], v[240:241]
	v_pk_fma_f32 v[98:99], v[98:99], v[142:143], v[238:239]
	global_load_dwordx4 v[238:241], v188, s[20:21]
	global_store_dwordx4 v178, v[98:101], s[16:17] nt
	s_waitcnt vmcnt(17)
	v_pk_fma_f32 v[96:97], v[96:97], v[144:145], v[194:195]
	v_pk_fma_f32 v[94:95], v[94:95], v[142:143], v[192:193]
	global_load_dwordx4 v[192:195], v180, s[20:21] offset:512
	global_store_dwordx4 v186, v[94:97], s[16:17] nt
	s_waitcnt vmcnt(17)
	v_pk_fma_f32 v[88:89], v[88:89], v[136:137], v[198:199]
	v_pk_fma_f32 v[86:87], v[86:87], v[134:135], v[196:197]
	global_load_dwordx4 v[196:199], v188, s[20:21] offset:512
	global_store_dwordx4 v178, v[86:89], s[16:17] offset:512 nt
	s_waitcnt vmcnt(17)
	v_pk_fma_f32 v[76:77], v[76:77], v[136:137], v[202:203]
	v_pk_fma_f32 v[74:75], v[74:75], v[134:135], v[200:201]
	global_load_dwordx4 v[200:203], v181, s[20:21]
	global_store_dwordx4 v186, v[74:77], s[16:17] offset:512 nt
	s_waitcnt vmcnt(17)
	v_pk_fma_f32 v[84:85], v[84:85], v[144:145], v[206:207]
	v_pk_fma_f32 v[82:83], v[82:83], v[142:143], v[204:205]
	global_load_dwordx4 v[204:207], v189, s[20:21]
	global_store_dwordx4 v179, v[82:85], s[16:17] nt
	s_waitcnt vmcnt(17)
	v_pk_fma_f32 v[80:81], v[80:81], v[144:145], v[210:211]
	v_pk_fma_f32 v[78:79], v[78:79], v[142:143], v[208:209]
	global_load_dwordx4 v[208:211], v181, s[20:21] offset:512
	global_store_dwordx4 v187, v[78:81], s[16:17] nt
	s_waitcnt vmcnt(17)
	v_pk_fma_f32 v[72:73], v[72:73], v[136:137], v[214:215]
	v_pk_fma_f32 v[70:71], v[70:71], v[134:135], v[212:213]
	global_load_dwordx4 v[212:215], v189, s[20:21] offset:512
	global_store_dwordx4 v179, v[70:73], s[16:17] offset:512 nt
	s_waitcnt vmcnt(17)
	v_pk_fma_f32 v[68:69], v[68:69], v[136:137], v[218:219]
	v_pk_fma_f32 v[66:67], v[66:67], v[134:135], v[216:217]
	global_load_dwordx4 v[216:219], v182, s[20:21]
	global_store_dwordx4 v187, v[66:69], s[16:17] offset:512 nt
	s_waitcnt vmcnt(17)
	v_pk_fma_f32 v[64:65], v[64:65], v[144:145], v[236:237]
	v_pk_fma_f32 v[62:63], v[62:63], v[142:143], v[234:235]
	global_load_dwordx4 v[234:237], v190, s[20:21]
	global_store_dwordx4 v180, v[62:65], s[16:17] nt
	s_waitcnt vmcnt(17)
	v_pk_fma_f32 v[60:61], v[60:61], v[144:145], v[240:241]
	v_pk_fma_f32 v[58:59], v[58:59], v[142:143], v[238:239]
	global_load_dwordx4 v[238:241], v182, s[20:21] offset:512
	global_store_dwordx4 v188, v[58:61], s[16:17] nt
	s_waitcnt vmcnt(17)
	v_pk_fma_f32 v[56:57], v[56:57], v[136:137], v[194:195]
	v_pk_fma_f32 v[54:55], v[54:55], v[134:135], v[192:193]
	global_load_dwordx4 v[192:195], v190, s[20:21] offset:512
	global_store_dwordx4 v180, v[54:57], s[16:17] offset:512 nt
	s_waitcnt vmcnt(17)
	v_pk_fma_f32 v[42:43], v[42:43], v[136:137], v[198:199]
	v_pk_fma_f32 v[40:41], v[40:41], v[134:135], v[196:197]
	global_load_dwordx4 v[196:199], v183, s[20:21]
	global_store_dwordx4 v188, v[40:43], s[16:17] offset:512 nt
	s_waitcnt vmcnt(17)
	v_pk_fma_f32 v[52:53], v[52:53], v[144:145], v[202:203]
	v_pk_fma_f32 v[50:51], v[50:51], v[142:143], v[200:201]
	global_load_dwordx4 v[200:203], v191, s[20:21]
	global_store_dwordx4 v181, v[50:53], s[16:17] nt
	s_waitcnt vmcnt(17)
	v_pk_fma_f32 v[46:47], v[46:47], v[144:145], v[206:207]
	v_pk_fma_f32 v[44:45], v[44:45], v[142:143], v[204:205]
	global_load_dwordx4 v[204:207], v183, s[20:21] offset:512
	global_store_dwordx4 v189, v[44:47], s[16:17] nt
	s_waitcnt vmcnt(17)
	v_pk_fma_f32 v[38:39], v[38:39], v[136:137], v[210:211]
	v_pk_fma_f32 v[36:37], v[36:37], v[134:135], v[208:209]
	global_load_dwordx4 v[208:211], v191, s[20:21] offset:512
	s_mov_b64 s[20:21], s[12:13]
	global_store_dwordx4 v181, v[36:39], s[16:17] offset:512 nt
	s_waitcnt vmcnt(17)
	v_pk_fma_f32 v[26:27], v[26:27], v[136:137], v[214:215]
	v_pk_fma_f32 v[24:25], v[24:25], v[134:135], v[212:213]
	global_store_dwordx4 v189, v[24:27], s[16:17] offset:512 nt
	s_waitcnt vmcnt(16)
	v_pk_fma_f32 v[34:35], v[34:35], v[144:145], v[218:219]
	v_pk_fma_f32 v[32:33], v[32:33], v[142:143], v[216:217]
	global_store_dwordx4 v182, v[32:35], s[16:17] nt
	s_waitcnt vmcnt(15)
	v_pk_fma_f32 v[30:31], v[30:31], v[144:145], v[236:237]
	v_pk_fma_f32 v[28:29], v[28:29], v[142:143], v[234:235]
	global_store_dwordx4 v190, v[28:31], s[16:17] nt
	s_waitcnt vmcnt(14)
	v_pk_fma_f32 v[22:23], v[22:23], v[136:137], v[240:241]
	v_pk_fma_f32 v[20:21], v[20:21], v[134:135], v[238:239]
	global_store_dwordx4 v182, v[20:23], s[16:17] offset:512 nt
	s_waitcnt vmcnt(13)
	v_pk_fma_f32 v[10:11], v[10:11], v[136:137], v[194:195]
	v_pk_fma_f32 v[8:9], v[8:9], v[134:135], v[192:193]
	global_store_dwordx4 v190, v[8:11], s[16:17] offset:512 nt
	s_waitcnt vmcnt(12)
	v_pk_fma_f32 v[18:19], v[18:19], v[144:145], v[198:199]
	v_pk_fma_f32 v[16:17], v[16:17], v[142:143], v[196:197]
	global_store_dwordx4 v183, v[16:19], s[16:17] nt
	s_waitcnt vmcnt(11)
	v_pk_fma_f32 v[14:15], v[14:15], v[144:145], v[202:203]
	v_pk_fma_f32 v[12:13], v[12:13], v[142:143], v[200:201]
	global_store_dwordx4 v191, v[12:15], s[16:17] nt
	s_waitcnt vmcnt(10)
	v_pk_fma_f32 v[6:7], v[6:7], v[136:137], v[206:207]
	v_pk_fma_f32 v[4:5], v[4:5], v[134:135], v[204:205]
	global_store_dwordx4 v183, v[4:7], s[16:17] offset:512 nt
	s_waitcnt vmcnt(9)
	v_pk_fma_f32 v[2:3], v[2:3], v[136:137], v[210:211]
	v_pk_fma_f32 v[0:1], v[0:1], v[134:135], v[208:209]
	global_store_dwordx4 v191, v[0:3], s[16:17] offset:512 nt
	s_mov_b64 s[16:17], s[2:3]
	s_and_b64 vcc, exec, s[40:41]
	s_cbranch_vccnz .LBB0_273
